# stack plus small CU-group stagger at GEMM phase entry
# speedup vs baseline: 1.0044x; 1.0044x over previous
.LBB0_227:
	s_load_dwordx16 s[4:19], s[0:1], 0x40
	s_waitcnt lgkmcnt(0)
	v_writelane_b32 v254, s4, 37
	s_nop 1
	v_writelane_b32 v254, s5, 38
	v_writelane_b32 v254, s6, 39
	v_writelane_b32 v254, s7, 40
	v_writelane_b32 v254, s8, 41
	v_writelane_b32 v254, s9, 42
	v_writelane_b32 v254, s10, 43
	v_writelane_b32 v254, s11, 44
	v_writelane_b32 v254, s12, 45
	v_writelane_b32 v254, s13, 46
	v_writelane_b32 v254, s14, 47
	v_writelane_b32 v254, s15, 48
	v_writelane_b32 v254, s16, 49
	v_writelane_b32 v254, s17, 50
	v_writelane_b32 v254, s18, 51
	v_writelane_b32 v254, s19, 52
	s_nop 0
	v_readlane_b32 s2, v254, 15
	v_readlane_b32 s3, v254, 16
	s_mul_i32 s0, s3, 0x23f0
	s_mul_hi_u32 s1, s2, 0x23f0
	s_add_i32 s1, s1, s0
	s_mul_i32 s0, s2, 0x23f0
	s_add_u32 s0, s58, s0
	s_addc_u32 s1, s59, s1
	s_add_u32 s0, s0, 0x100000
	s_addc_u32 s1, s1, 0
	v_writelane_b32 v254, s0, 53
	s_nop 1
	v_writelane_b32 v254, s1, 54
	s_nop 0
	v_readlane_b32 s4, v254, 13
	v_readlane_b32 s5, v254, 14
	s_cmp_lt_i32 s4, 2
	s_cselect_b64 s[0:1], -1, 0
	s_cmp_gt_i32 s5, 1
	s_cselect_b64 s[2:3], -1, 0
	s_and_b64 s[0:1], s[0:1], s[2:3]
	s_andn2_b64 vcc, exec, s[0:1]
	s_cbranch_vccnz .LBB0_379
	v_readlane_b32 s98, v254, 53
	v_readlane_b32 s99, v254, 54
	s_load_dword s100, s[98:99], 0x0
	s_load_dword s101, s[98:99], 0x40
	s_load_dword s100, s[98:99], 0x80
	s_load_dword s101, s[98:99], 0xc0
	s_load_dword s100, s[98:99], 0x100
	s_load_dword s101, s[98:99], 0x140
	s_load_dword s100, s[98:99], 0x180
	s_load_dword s101, s[98:99], 0x1c0
	s_load_dword s100, s[98:99], 0x200
	s_load_dword s101, s[98:99], 0x240
	s_load_dword s100, s[98:99], 0x280
	s_load_dword s101, s[98:99], 0x2c0
	s_load_dword s100, s[98:99], 0x300
	s_load_dword s101, s[98:99], 0x340
	s_load_dword s100, s[98:99], 0x380
	s_load_dword s101, s[98:99], 0x3c0
	s_load_dword s100, s[98:99], 0x400
	s_load_dword s101, s[98:99], 0x440
	s_load_dword s100, s[98:99], 0x480
	s_load_dword s101, s[98:99], 0x4c0
	s_load_dword s100, s[98:99], 0x500
	s_load_dword s101, s[98:99], 0x540
	s_load_dword s100, s[98:99], 0x580
	s_load_dword s101, s[98:99], 0x5c0
	s_load_dword s100, s[98:99], 0x600
	s_load_dword s101, s[98:99], 0x640
	s_load_dword s100, s[98:99], 0x680
	s_load_dword s101, s[98:99], 0x6c0
	s_load_dword s100, s[98:99], 0x700
	s_load_dword s101, s[98:99], 0x740
	s_load_dword s100, s[98:99], 0x780
	s_load_dword s101, s[98:99], 0x7c0
	s_load_dword s100, s[98:99], 0x800
	s_load_dword s101, s[98:99], 0x840
	s_load_dword s100, s[98:99], 0x880
	s_load_dword s101, s[98:99], 0x8c0
	s_load_dword s100, s[98:99], 0x900
	s_load_dword s101, s[98:99], 0x940
	s_load_dword s100, s[98:99], 0x980
	s_load_dword s101, s[98:99], 0x9c0
	s_waitcnt lgkmcnt(0)
	s_getreg_b32 s98, hwreg(HW_REG_HW_ID, 8, 2)
	s_cmp_eq_u32 s98, 0
	s_cbranch_scc1 .Lstg_done_p1
.Lstg_loop_p1:
	s_sleep 64
	s_sub_u32 s98, s98, 1
	s_cmp_lg_u32 s98, 0
	s_cbranch_scc1 .Lstg_loop_p1
.Lstg_done_p1:
	v_readlane_b32 s12, v254, 53
	v_readlane_b32 s0, v254, 0
	v_readlane_b32 s13, v254, 54
	s_lshr_b32 s56, s0, 8
	v_mbcnt_lo_u32_b32 v2, -1, 0
	v_mbcnt_hi_u32_b32 v2, -1, v2
	s_lshl_b32 s0, s76, 5
	s_load_dwordx2 s[18:19], s[12:13], 0x30
	s_and_b32 s52, s0, 0x60
	s_lshr_b32 s0, s52, 3
	v_writelane_b32 v254, s0, 55
	s_lshl_b32 s0, s76, 10
	s_lshl_b32 s3, s56, 6
	s_lshl_b32 s95, s56, 13
	s_add_i32 s53, s0, 0
	s_waitcnt lgkmcnt(0)
	s_cmp_eq_u32 s18, 0
	s_mov_b32 s9, 0
	s_cbranch_scc1 .LBB0_247
	s_load_dwordx4 s[4:7], s[12:13], 0x0
	s_load_dwordx2 s[36:37], s[12:13], 0x10
	s_load_dwordx2 s[0:1], s[12:13], 0x3c
	s_waitcnt lgkmcnt(0)
	v_readlane_b32 s1, v254, 0
	s_andn2_b32 s1, s1, 63
	v_mbcnt_lo_u32_b32 v0, -1, 0
	v_mbcnt_hi_u32_b32 v0, -1, v0
	s_load_dwordx2 s[10:11], s[12:13], 0x28
	v_add_u32_e32 v0, s1, v0
	v_ashrrev_i32_e32 v3, 31, v0
	v_lshrrev_b32_e32 v3, 26, v3
	v_lshlrev_b32_e32 v1, 4, v0
	v_add_u32_e32 v3, v0, v3
	v_bfe_i32 v0, v0, 27, 1
	v_lshrrev_b32_e32 v0, 22, v0
	v_add_u32_e32 v0, v1, v0
	v_and_b32_e32 v0, 0xfffffc00, v0
	v_sub_u32_e32 v0, v1, v0
	v_lshrrev_b32_e32 v1, 4, v0
	v_bitop3_b32 v0, v1, v0, 32 bitop3:0x6c
	v_ashrrev_i32_e32 v4, 31, v0
	v_lshrrev_b32_e32 v4, 26, v4
	v_add_u32_e32 v4, v0, v4
	v_ashrrev_i32_e32 v5, 6, v4
	v_and_b32_e32 v4, 0xc0, v4
	v_ashrrev_i32_e32 v3, 6, v3
	v_sub_u32_e32 v0, v0, v4
	v_mov_b32_e32 v190, 1
	v_lshlrev_b32_e32 v1, 3, v3
	v_lshlrev_b32_e32 v3, 5, v3
	v_ashrrev_i16_sdwa v0, v190, sext(v0) dst_sel:DWORD dst_unused:UNUSED_PAD src0_sel:DWORD src1_sel:BYTE_0
	v_and_b32_e32 v1, -16, v1
	v_and_b32_e32 v3, 32, v3
	v_bfe_i32 v0, v0, 0, 16
	v_add_lshl_u32 v4, v3, v0, 1
	v_add_u32_e32 v3, v5, v1
	v_and_b32_e32 v6, 3, v5
	v_lshlrev_b32_e32 v0, 1, v3
	v_lshrrev_b32_e32 v1, 2, v3
	s_movk_i32 s50, 0xffe0
	s_waitcnt lgkmcnt(0)
	s_mov_b32 s8, s10
	s_mov_b32 s22, s11
	s_mov_b32 s23, s9
	v_and_b32_e32 v0, 24, v0
	v_and_b32_e32 v1, 4, v1
	v_and_or_b32 v5, v3, s50, v6
	s_lshl_b64 s[38:39], s[8:9], 6
	s_lshl_b64 s[16:17], s[22:23], 6
	v_or3_b32 v0, v5, v1, v0
	v_mad_u64_u32 v[160:161], s[12:13], v3, s10, v[4:5]
	s_add_u32 s10, s6, s16
	v_mad_u64_u32 v[0:1], s[12:13], v0, s11, v[4:5]
	s_addc_u32 s11, s7, s17
	s_add_i32 s51, s53, 0x10000
	s_mov_b32 m0, s51
	s_nop 0
	global_load_lds_dwordx4 v0, s[6:7]
	s_add_i32 s57, s53, 0x12000
	s_mov_b32 m0, s57
	s_nop 0
	global_load_lds_dwordx4 v0, s[10:11]
	s_add_u32 s10, s10, s16
	s_addc_u32 s11, s11, s17
	s_add_u32 s12, s10, s16
	s_addc_u32 s13, s11, s17
	s_add_i32 s58, s53, 0x14000
	s_mov_b32 m0, s58
	s_nop 0
	global_load_lds_dwordx4 v0, s[10:11]
	s_add_i32 s59, s53, 0x16000
	s_mov_b32 m0, s59
	s_nop 0
	global_load_lds_dwordx4 v0, s[12:13]
	s_add_u32 s14, s4, s38
	s_addc_u32 s15, s5, s39
	s_mov_b32 m0, s53
	s_nop 0
	global_load_lds_dwordx4 v160, s[4:5]
	s_add_i32 s60, s53, 0x2000
	s_mov_b32 m0, s60
	s_nop 0
	global_load_lds_dwordx4 v160, s[14:15]
	s_add_u32 s14, s14, s38
	s_addc_u32 s15, s15, s39
	s_add_u32 s24, s14, s38
	s_addc_u32 s25, s15, s39
	s_add_i32 s61, s53, 0x4000
	s_mov_b32 m0, s61
	s_nop 0
	global_load_lds_dwordx4 v160, s[14:15]
	s_add_i32 s62, s53, 0x6000
	s_mov_b32 m0, s62
	s_nop 0
	global_load_lds_dwordx4 v160, s[24:25]
	s_cmp_eq_u32 s56, 1
	s_cselect_b64 s[20:21], -1, 0
	s_cmp_lg_u32 s56, 1
	s_cbranch_scc1 .LBB0_231
	s_barrier

.LBB0_672:
	s_cmp_lt_i32 s4, 6
	s_cselect_b64 s[0:1], -1, 0
	s_cmp_gt_i32 s5, 5
	s_cselect_b64 s[2:3], -1, 0
	s_and_b64 s[0:1], s[0:1], s[2:3]
	s_andn2_b64 vcc, exec, s[0:1]
	s_cbranch_vccnz .LBB0_772
	v_readlane_b32 s98, v254, 53
	v_readlane_b32 s99, v254, 54
	s_load_dword s100, s[98:99], 0x9b0
	s_load_dword s101, s[98:99], 0x9f0
	s_load_dword s100, s[98:99], 0xa30
	s_load_dword s101, s[98:99], 0xa70
	s_load_dword s100, s[98:99], 0xab0
	s_load_dword s101, s[98:99], 0xaf0
	s_load_dword s100, s[98:99], 0xb30
	s_load_dword s101, s[98:99], 0xb70
	s_load_dword s100, s[98:99], 0xbb0
	s_load_dword s101, s[98:99], 0xbf0
	s_load_dword s100, s[98:99], 0xc30
	s_load_dword s101, s[98:99], 0xc70
	s_load_dword s100, s[98:99], 0xcb0
	s_load_dword s101, s[98:99], 0xcf0
	s_load_dword s100, s[98:99], 0xd30
	s_load_dword s101, s[98:99], 0xd70
	s_waitcnt lgkmcnt(0)
	s_getreg_b32 s98, hwreg(HW_REG_HW_ID, 8, 2)
	s_cmp_eq_u32 s98, 0
	s_cbranch_scc1 .Lstg_done_p3

.Lstg_done_p3:
	v_readlane_b32 s12, v254, 53
	v_readlane_b32 s13, v254, 54
	v_mbcnt_lo_u32_b32 v2, -1, 0
	v_mbcnt_hi_u32_b32 v2, -1, v2
	s_load_dwordx2 s[18:19], s[12:13], 0x9e0
	s_add_u32 s10, s12, 0x9b0
	v_readlane_b32 s0, v254, 0
	s_addc_u32 s11, s13, 0
	s_lshr_b32 s54, s0, 8
	s_lshl_b32 s0, s76, 5
	s_and_b32 s56, s0, 0x60
	s_lshl_b32 s0, s76, 10
	s_lshl_b32 s3, s54, 6
	s_lshl_b32 s50, s54, 13
	s_lshr_b32 s51, s56, 3
	s_add_i32 s57, s0, 0
	s_waitcnt lgkmcnt(0)
	s_cmp_eq_u32 s18, 0
	s_mov_b32 s9, 0
	s_cbranch_scc1 .LBB0_692
	v_readlane_b32 s2, v254, 0
	s_load_dwordx4 s[4:7], s[10:11], 0x0
	s_load_dwordx2 s[36:37], s[10:11], 0x10
	s_load_dwordx2 s[0:1], s[10:11], 0x3c
	s_and_b32 s52, s2, 0xffffffc0
	v_mbcnt_lo_u32_b32 v0, -1, 0
	v_mbcnt_hi_u32_b32 v0, -1, v0
	s_load_dwordx2 s[10:11], s[12:13], 0x9d8
	v_add_u32_e32 v0, s52, v0
	v_ashrrev_i32_e32 v3, 31, v0
	v_lshrrev_b32_e32 v3, 26, v3
	v_lshlrev_b32_e32 v1, 4, v0
	v_add_u32_e32 v3, v0, v3
	v_bfe_i32 v0, v0, 27, 1
	v_lshrrev_b32_e32 v0, 22, v0
	v_add_u32_e32 v0, v1, v0
	v_and_b32_e32 v0, 0xfffffc00, v0
	v_sub_u32_e32 v0, v1, v0
	v_lshrrev_b32_e32 v1, 4, v0
	v_bitop3_b32 v0, v1, v0, 32 bitop3:0x6c
	v_ashrrev_i32_e32 v4, 31, v0
	v_lshrrev_b32_e32 v4, 26, v4
	v_add_u32_e32 v4, v0, v4
	v_ashrrev_i32_e32 v5, 6, v4
	v_and_b32_e32 v4, 0xc0, v4
	v_ashrrev_i32_e32 v3, 6, v3
	v_sub_u32_e32 v0, v0, v4
	v_mov_b32_e32 v134, 1
	v_lshlrev_b32_e32 v1, 3, v3
	v_lshlrev_b32_e32 v3, 5, v3
	v_ashrrev_i16_sdwa v0, v134, sext(v0) dst_sel:DWORD dst_unused:UNUSED_PAD src0_sel:DWORD src1_sel:BYTE_0
	v_and_b32_e32 v1, -16, v1
	v_and_b32_e32 v3, 32, v3
	v_bfe_i32 v0, v0, 0, 16
	v_add_lshl_u32 v4, v3, v0, 1
	v_add_u32_e32 v3, v5, v1
	v_and_b32_e32 v6, 3, v5
	v_lshlrev_b32_e32 v0, 1, v3
	v_lshrrev_b32_e32 v1, 2, v3
	s_movk_i32 s53, 0xffe0
	s_waitcnt lgkmcnt(0)
	s_mov_b32 s8, s10
	s_mov_b32 s22, s11
	s_mov_b32 s23, s9
	v_and_b32_e32 v0, 24, v0
	v_and_b32_e32 v1, 4, v1
	v_and_or_b32 v5, v3, s53, v6
	s_lshl_b64 s[38:39], s[8:9], 6
	s_lshl_b64 s[16:17], s[22:23], 6
	v_or3_b32 v0, v5, v1, v0
	v_mad_u64_u32 v[128:129], s[12:13], v3, s10, v[4:5]
	s_add_u32 s10, s6, s16
	v_mad_u64_u32 v[0:1], s[12:13], v0, s11, v[4:5]
	s_addc_u32 s11, s7, s17
	s_add_i32 s55, s57, 0x10000
	s_mov_b32 m0, s55
	s_nop 0
	global_load_lds_dwordx4 v0, s[6:7]
	s_add_i32 s58, s57, 0x12000
	s_mov_b32 m0, s58
	s_nop 0
	global_load_lds_dwordx4 v0, s[10:11]
	s_add_u32 s10, s10, s16
	s_addc_u32 s11, s11, s17
	s_add_u32 s12, s10, s16
	s_addc_u32 s13, s11, s17
	s_add_i32 s2, s57, 0x14000
	s_mov_b32 m0, s2
	s_nop 0
	global_load_lds_dwordx4 v0, s[10:11]
	s_add_i32 s59, s57, 0x16000
	s_mov_b32 m0, s59
	s_nop 0
	global_load_lds_dwordx4 v0, s[12:13]
	s_add_u32 s14, s4, s38
	s_addc_u32 s15, s5, s39
	s_mov_b32 m0, s57
	s_nop 0
	global_load_lds_dwordx4 v128, s[4:5]
	s_add_i32 s60, s57, 0x2000
	s_mov_b32 m0, s60
	s_nop 0
	global_load_lds_dwordx4 v128, s[14:15]
	s_add_u32 s14, s14, s38
	s_addc_u32 s15, s15, s39
	s_add_u32 s24, s14, s38
	s_addc_u32 s25, s15, s39
	s_add_i32 s33, s57, 0x4000
	s_mov_b32 m0, s33
	s_nop 0
	global_load_lds_dwordx4 v128, s[14:15]
	s_add_i32 s61, s57, 0x6000
	s_mov_b32 m0, s61
	s_nop 0
	global_load_lds_dwordx4 v128, s[24:25]
	s_cmp_eq_u32 s54, 1
	s_cselect_b64 s[20:21], -1, 0
	s_cmp_lg_u32 s54, 1
	s_cbranch_scc1 .LBB0_676
	s_barrier

.LBB0_772:
	s_cmp_lt_i32 s4, 7
	s_cselect_b64 s[0:1], -1, 0
	s_cmp_gt_i32 s5, 6
	s_cselect_b64 s[2:3], -1, 0
	s_and_b64 s[0:1], s[0:1], s[2:3]
	s_andn2_b64 vcc, exec, s[0:1]
	s_cbranch_vccnz .LBB0_848
	v_readlane_b32 s98, v254, 53
	v_readlane_b32 s99, v254, 54
	s_load_dword s100, s[98:99], 0xd70
	s_load_dword s101, s[98:99], 0xdb0
	s_load_dword s100, s[98:99], 0xdf0
	s_load_dword s101, s[98:99], 0xe30
	s_load_dword s100, s[98:99], 0xe70
	s_load_dword s101, s[98:99], 0xeb0
	s_waitcnt lgkmcnt(0)
	s_getreg_b32 s98, hwreg(HW_REG_HW_ID, 8, 2)
	s_cmp_eq_u32 s98, 0
	s_cbranch_scc1 .Lstg_done_p4

.Lstg_done_p4:
	v_readlane_b32 s0, v254, 53
	v_readlane_b32 s1, v254, 54
	v_mbcnt_lo_u32_b32 v2, -1, 0
	v_mbcnt_hi_u32_b32 v2, -1, v2
	s_load_dwordx4 s[24:27], s[0:1], 0xda0
	s_add_u32 s0, s0, 0xd70
	s_addc_u32 s1, s1, 0
	s_mov_b32 s17, 0
	s_waitcnt lgkmcnt(0)
	s_cmp_eq_u32 s24, 0
	s_cbranch_scc1 .LBB0_792
	v_readlane_b32 s12, v254, 0
	s_load_dwordx8 s[4:11], s[0:1], 0x0
	s_and_b32 s56, s12, 0xffffffc0
	v_mbcnt_lo_u32_b32 v0, -1, 0
	v_mbcnt_hi_u32_b32 v0, -1, v0
	s_lshr_b32 s2, s12, 8
	v_add_u32_e32 v0, s56, v0
	v_ashrrev_i32_e32 v3, 31, v0
	v_lshrrev_b32_e32 v3, 26, v3
	v_lshlrev_b32_e32 v1, 4, v0
	v_add_u32_e32 v3, v0, v3
	v_bfe_i32 v0, v0, 27, 1
	v_lshrrev_b32_e32 v0, 22, v0
	v_add_u32_e32 v0, v1, v0
	v_and_b32_e32 v0, 0xfffffc00, v0
	v_sub_u32_e32 v0, v1, v0
	v_lshrrev_b32_e32 v1, 4, v0
	v_bitop3_b32 v0, v1, v0, 32 bitop3:0x6c
	v_ashrrev_i32_e32 v4, 31, v0
	v_lshrrev_b32_e32 v4, 26, v4
	v_add_u32_e32 v4, v0, v4
	v_ashrrev_i32_e32 v5, 6, v4
	v_and_b32_e32 v4, 0xc0, v4
	v_readlane_b32 s12, v254, 53
	v_ashrrev_i32_e32 v3, 6, v3
	v_sub_u32_e32 v0, v0, v4
	v_mov_b32_e32 v136, 1
	v_readlane_b32 s13, v254, 54
	v_lshlrev_b32_e32 v1, 3, v3
	v_lshlrev_b32_e32 v3, 5, v3
	v_ashrrev_i16_sdwa v0, v136, sext(v0) dst_sel:DWORD dst_unused:UNUSED_PAD src0_sel:DWORD src1_sel:BYTE_0
	s_load_dwordx2 s[0:1], s[12:13], 0xd98
	v_and_b32_e32 v1, -16, v1
	v_and_b32_e32 v3, 32, v3
	v_bfe_i32 v0, v0, 0, 16
	v_add_lshl_u32 v4, v3, v0, 1
	v_add_u32_e32 v3, v5, v1
	v_and_b32_e32 v6, 3, v5
	v_lshlrev_b32_e32 v0, 1, v3
	v_lshrrev_b32_e32 v1, 2, v3
	s_movk_i32 s12, 0xffe0
	v_and_b32_e32 v0, 24, v0
	v_and_b32_e32 v1, 4, v1
	v_and_or_b32 v5, v3, s12, v6
	s_lshl_b32 s3, s76, 10
	v_or3_b32 v0, v5, v1, v0
	s_waitcnt lgkmcnt(0)
	s_mov_b32 s16, s0
	s_mov_b32 s20, s1
	s_mov_b32 s21, s17
	s_add_i32 s3, s3, 0
	v_mad_u64_u32 v[0:1], s[12:13], v0, s1, v[4:5]
	v_mad_u64_u32 v[128:129], s[12:13], v3, s0, v[4:5]
	s_lshl_b64 s[46:47], s[16:17], 6
	s_lshl_b64 s[0:1], s[20:21], 6
	s_add_u32 s12, s6, s0
	s_addc_u32 s13, s7, s1
	s_add_i32 s58, s3, 0x10000
	s_mov_b32 m0, s58
	s_nop 0
	global_load_lds_dwordx4 v0, s[6:7]
	s_add_i32 s59, s3, 0x12000
	s_mov_b32 m0, s59
	s_nop 0
	global_load_lds_dwordx4 v0, s[12:13]
	s_add_u32 s12, s12, s0
	s_addc_u32 s13, s13, s1
	s_add_u32 s14, s12, s0
	s_addc_u32 s15, s13, s1
	s_add_i32 s60, s3, 0x14000
	s_mov_b32 m0, s60
	s_nop 0
	global_load_lds_dwordx4 v0, s[12:13]
	s_add_i32 s61, s3, 0x16000
	s_mov_b32 m0, s61
	s_nop 0
	global_load_lds_dwordx4 v0, s[14:15]
	s_add_u32 s18, s4, s46
	s_addc_u32 s19, s5, s47
	s_mov_b32 m0, s3
	s_nop 0
	global_load_lds_dwordx4 v128, s[4:5]
	s_add_i32 s62, s3, 0x2000
	s_mov_b32 m0, s62
	s_nop 0
	global_load_lds_dwordx4 v128, s[18:19]
	s_add_u32 s18, s18, s46
	s_addc_u32 s19, s19, s47
	s_add_u32 s22, s18, s46
	s_addc_u32 s23, s19, s47
	s_add_i32 s63, s3, 0x4000
	s_mov_b32 m0, s63
	s_nop 0
	global_load_lds_dwordx4 v128, s[18:19]
	s_add_i32 s64, s3, 0x6000
	s_mov_b32 m0, s64
	s_nop 0
	global_load_lds_dwordx4 v128, s[22:23]
	s_cmp_eq_u32 s2, 1
	s_cselect_b64 s[28:29], -1, 0
	s_cmp_lg_u32 s2, 1
	s_cbranch_scc1 .LBB0_776
	s_barrier

.LBB0_912:
	s_cmp_lt_i32 s4, 9
	s_cselect_b64 s[0:1], -1, 0
	s_cmp_gt_i32 s5, 8
	s_cselect_b64 s[2:3], -1, 0
	s_and_b64 s[0:1], s[0:1], s[2:3]
	s_andn2_b64 vcc, exec, s[0:1]
	s_cbranch_vccnz .LBB0_1007
	v_readlane_b32 s98, v254, 53
	v_readlane_b32 s99, v254, 54
	s_load_dword s100, s[98:99], 0xeb0
	s_load_dword s101, s[98:99], 0xef0
	s_load_dword s100, s[98:99], 0xf30
	s_load_dword s101, s[98:99], 0xf70
	s_load_dword s100, s[98:99], 0xfb0
	s_load_dword s101, s[98:99], 0xff0
	s_load_dword s100, s[98:99], 0x1030
	s_load_dword s101, s[98:99], 0x1070
	s_load_dword s100, s[98:99], 0x10b0
	s_load_dword s101, s[98:99], 0x10f0
	s_load_dword s100, s[98:99], 0x1130
	s_load_dword s101, s[98:99], 0x1170
	s_load_dword s100, s[98:99], 0x11b0
	s_load_dword s101, s[98:99], 0x11f0
	s_load_dword s100, s[98:99], 0x1230
	s_load_dword s101, s[98:99], 0x1270
	s_load_dword s100, s[98:99], 0x12b0
	s_load_dword s101, s[98:99], 0x12f0
	s_load_dword s100, s[98:99], 0x1330
	s_load_dword s101, s[98:99], 0x1370
	s_load_dword s100, s[98:99], 0x13b0
	s_load_dword s101, s[98:99], 0x13f0
	s_load_dword s100, s[98:99], 0x1430
	s_load_dword s101, s[98:99], 0x1470
	s_load_dword s100, s[98:99], 0x14b0
	s_load_dword s101, s[98:99], 0x14f0
	s_load_dword s100, s[98:99], 0x1530
	s_load_dword s101, s[98:99], 0x1570
	s_load_dword s100, s[98:99], 0x15b0
	s_load_dword s101, s[98:99], 0x15f0
	s_load_dword s100, s[98:99], 0x1630
	s_load_dword s101, s[98:99], 0x1670
	s_load_dword s100, s[98:99], 0x16b0
	s_load_dword s101, s[98:99], 0x16f0
	s_load_dword s100, s[98:99], 0x1730
	s_waitcnt lgkmcnt(0)
	s_getreg_b32 s98, hwreg(HW_REG_HW_ID, 8, 2)
	s_cmp_eq_u32 s98, 0
	s_cbranch_scc1 .Lstg_done_p5

.Lstg_done_p5:
	v_readlane_b32 s12, v254, 53
	v_readlane_b32 s13, v254, 54
	s_add_u32 s10, s12, 0xeb0
	v_readlane_b32 s0, v254, 0
	s_addc_u32 s11, s13, 0
	s_lshr_b32 s48, s0, 8
	v_mbcnt_lo_u32_b32 v2, -1, 0
	v_mbcnt_hi_u32_b32 v2, -1, v2
	s_load_dwordx2 s[0:1], s[12:13], 0xee0
	s_lshl_b32 s2, s76, 5
	s_and_b32 s54, s2, 0x60
	s_lshl_b32 s2, s76, 10
	s_lshl_b32 s3, s48, 6
	s_lshl_b32 s46, s48, 13
	s_lshr_b32 s47, s54, 3
	s_add_i32 s55, s2, 0
	s_waitcnt lgkmcnt(0)
	s_cmp_eq_u32 s0, 0
	s_mov_b32 s9, 0
	s_cbranch_scc1 .LBB0_932
	v_readlane_b32 s2, v254, 0
	s_load_dwordx4 s[4:7], s[10:11], 0x0
	s_load_dwordx2 s[30:31], s[10:11], 0x10
	s_and_b32 s49, s2, 0xffffffc0
	v_mbcnt_lo_u32_b32 v0, -1, 0
	v_mbcnt_hi_u32_b32 v0, -1, v0
	s_load_dwordx2 s[10:11], s[12:13], 0xed8
	v_add_u32_e32 v0, s49, v0
	v_ashrrev_i32_e32 v3, 31, v0
	v_lshrrev_b32_e32 v3, 26, v3
	v_lshlrev_b32_e32 v1, 4, v0
	v_add_u32_e32 v3, v0, v3
	v_bfe_i32 v0, v0, 27, 1
	v_lshrrev_b32_e32 v0, 22, v0
	v_add_u32_e32 v0, v1, v0
	v_and_b32_e32 v0, 0xfffffc00, v0
	v_sub_u32_e32 v0, v1, v0
	v_lshrrev_b32_e32 v1, 4, v0
	v_bitop3_b32 v0, v1, v0, 32 bitop3:0x6c
	v_ashrrev_i32_e32 v4, 31, v0
	v_lshrrev_b32_e32 v4, 26, v4
	v_add_u32_e32 v4, v0, v4
	v_ashrrev_i32_e32 v5, 6, v4
	v_and_b32_e32 v4, 0xc0, v4
	v_ashrrev_i32_e32 v3, 6, v3
	v_sub_u32_e32 v0, v0, v4
	v_mov_b32_e32 v132, 1
	v_lshlrev_b32_e32 v1, 3, v3
	v_lshlrev_b32_e32 v3, 5, v3
	v_ashrrev_i16_sdwa v0, v132, sext(v0) dst_sel:DWORD dst_unused:UNUSED_PAD src0_sel:DWORD src1_sel:BYTE_0
	v_and_b32_e32 v1, -16, v1
	v_and_b32_e32 v3, 32, v3
	v_bfe_i32 v0, v0, 0, 16
	v_add_lshl_u32 v4, v3, v0, 1
	v_add_u32_e32 v3, v5, v1
	v_and_b32_e32 v6, 3, v5
	v_lshlrev_b32_e32 v0, 1, v3
	v_lshrrev_b32_e32 v1, 2, v3
	s_movk_i32 s50, 0xffe0
	s_waitcnt lgkmcnt(0)
	s_mov_b32 s8, s10
	s_mov_b32 s20, s11
	s_mov_b32 s21, s9
	v_and_b32_e32 v0, 24, v0
	v_and_b32_e32 v1, 4, v1
	v_and_or_b32 v5, v3, s50, v6
	s_lshl_b64 s[34:35], s[8:9], 6
	s_lshl_b64 s[16:17], s[20:21], 6
	v_or3_b32 v0, v5, v1, v0
	v_mad_u64_u32 v[128:129], s[12:13], v3, s10, v[4:5]
	s_add_u32 s10, s6, s16
	v_mad_u64_u32 v[0:1], s[12:13], v0, s11, v[4:5]
	s_addc_u32 s11, s7, s17
	s_add_i32 s51, s55, 0x10000
	s_mov_b32 m0, s51
	s_nop 0
	global_load_lds_dwordx4 v0, s[6:7]
	s_add_i32 s52, s55, 0x12000
	s_mov_b32 m0, s52
	s_nop 0
	global_load_lds_dwordx4 v0, s[10:11]
	s_add_u32 s10, s10, s16
	s_addc_u32 s11, s11, s17
	s_add_u32 s12, s10, s16
	s_addc_u32 s13, s11, s17
	s_add_i32 s53, s55, 0x14000
	s_mov_b32 m0, s53
	s_nop 0
	global_load_lds_dwordx4 v0, s[10:11]
	s_add_i32 s56, s55, 0x16000
	s_mov_b32 m0, s56
	s_nop 0
	global_load_lds_dwordx4 v0, s[12:13]
	s_add_u32 s14, s4, s34
	s_addc_u32 s15, s5, s35
	s_mov_b32 m0, s55
	s_nop 0
	global_load_lds_dwordx4 v128, s[4:5]
	s_add_i32 s57, s55, 0x2000
	s_mov_b32 m0, s57
	s_nop 0
	global_load_lds_dwordx4 v128, s[14:15]
	s_add_u32 s14, s14, s34
	s_addc_u32 s15, s15, s35
	s_add_u32 s22, s14, s34
	s_addc_u32 s23, s15, s35
	s_add_i32 s58, s55, 0x4000
	s_mov_b32 m0, s58
	s_nop 0
	global_load_lds_dwordx4 v128, s[14:15]
	s_add_i32 s59, s55, 0x6000
	s_mov_b32 m0, s59
	s_nop 0
	global_load_lds_dwordx4 v128, s[22:23]
	s_cmp_eq_u32 s48, 1
	s_cselect_b64 s[18:19], -1, 0
	s_cmp_lg_u32 s48, 1
	s_cbranch_scc1 .LBB0_916
	s_barrier

.LBB0_1007:
	s_cmp_lt_i32 s4, 10
	s_cselect_b64 s[0:1], -1, 0
	s_cmp_gt_i32 s5, 9
	s_cselect_b64 s[2:3], -1, 0
	s_and_b64 s[0:1], s[0:1], s[2:3]
	s_andn2_b64 vcc, exec, s[0:1]
	s_cbranch_vccnz .LBB0_1084
	v_readlane_b32 s98, v254, 53
	v_readlane_b32 s99, v254, 54
	s_load_dword s100, s[98:99], 0x1720
	s_load_dword s101, s[98:99], 0x1760
	s_load_dword s100, s[98:99], 0x17a0
	s_load_dword s101, s[98:99], 0x17e0
	s_load_dword s100, s[98:99], 0x1820
	s_load_dword s101, s[98:99], 0x1860
	s_waitcnt lgkmcnt(0)
	s_getreg_b32 s98, hwreg(HW_REG_HW_ID, 8, 2)
	s_cmp_eq_u32 s98, 0
	s_cbranch_scc1 .Lstg_done_p6

.Lstg_done_p6:
	v_readlane_b32 s0, v254, 53
	v_readlane_b32 s1, v254, 54
	v_mbcnt_lo_u32_b32 v2, -1, 0
	v_mbcnt_hi_u32_b32 v2, -1, v2
	s_load_dword s2, s[0:1], 0x1750
	s_add_u32 s26, s0, 0x1720
	s_addc_u32 s27, s1, 0
	s_mov_b32 s13, 0
	s_waitcnt lgkmcnt(0)
	s_cmp_eq_u32 s2, 0
	s_cbranch_scc1 .LBB0_1028
	v_readlane_b32 s0, v254, 0
	s_lshr_b32 s18, s0, 8
	s_load_dwordx4 s[4:7], s[26:27], 0x0
	s_load_dwordx4 s[28:31], s[26:27], 0x18
	s_load_dwordx4 s[8:11], s[26:27], 0x38
	s_andn2_b32 s0, s0, 63
	v_mbcnt_lo_u32_b32 v0, -1, 0
	v_mbcnt_hi_u32_b32 v0, -1, v0
	v_mov_b32_e32 v172, 1
	v_add_u32_e32 v0, s0, v0
	v_ashrrev_i32_e32 v3, 31, v0
	v_lshrrev_b32_e32 v3, 26, v3
	v_lshlrev_b32_e32 v1, 4, v0
	v_add_u32_e32 v3, v0, v3
	v_bfe_i32 v0, v0, 27, 1
	v_lshrrev_b32_e32 v0, 22, v0
	v_add_u32_e32 v0, v1, v0
	v_and_b32_e32 v0, 0xfffffc00, v0
	v_sub_u32_e32 v0, v1, v0
	v_lshrrev_b32_e32 v1, 4, v0
	v_bitop3_b32 v0, v1, v0, 32 bitop3:0x6c
	v_ashrrev_i32_e32 v4, 31, v0
	v_lshrrev_b32_e32 v4, 26, v4
	v_add_u32_e32 v4, v0, v4
	v_ashrrev_i32_e32 v5, 6, v4
	v_and_b32_e32 v4, 0xc0, v4
	v_ashrrev_i32_e32 v3, 6, v3
	v_sub_u32_e32 v0, v0, v4
	v_lshlrev_b32_e32 v1, 3, v3
	v_lshlrev_b32_e32 v3, 5, v3
	v_ashrrev_i16_sdwa v0, v172, sext(v0) dst_sel:DWORD dst_unused:UNUSED_PAD src0_sel:DWORD src1_sel:BYTE_0
	v_and_b32_e32 v1, -16, v1
	v_and_b32_e32 v3, 32, v3
	v_bfe_i32 v0, v0, 0, 16
	s_load_dwordx2 s[14:15], s[26:27], 0x28
	v_add_lshl_u32 v4, v3, v0, 1
	v_add_u32_e32 v3, v5, v1
	s_mov_b32 s1, s0
	v_and_b32_e32 v6, 3, v5
	v_lshlrev_b32_e32 v0, 1, v3
	v_lshrrev_b32_e32 v1, 2, v3
	s_movk_i32 s0, 0xffe0
	v_and_b32_e32 v0, 24, v0
	v_and_b32_e32 v1, 4, v1
	v_and_or_b32 v5, v3, s0, v6
	v_or3_b32 v0, v5, v1, v0
	s_waitcnt lgkmcnt(0)
	v_mad_u64_u32 v[0:1], s[16:17], v0, s15, v[4:5]
	v_mad_u64_u32 v[128:129], s[16:17], v3, s14, v[4:5]
	s_lshl_b32 s3, s76, 10
	s_mov_b32 s12, s14
	s_mov_b32 s16, s15
	s_mov_b32 s17, s13
	s_add_i32 s3, s3, 0
	s_lshl_b64 s[52:53], s[12:13], 6
	s_lshl_b64 s[34:35], s[16:17], 6
	s_add_u32 s14, s6, s34
	s_addc_u32 s15, s7, s35
	s_add_i32 s62, s3, 0x10000
	s_mov_b32 m0, s62
	s_nop 0
	global_load_lds_dwordx4 v0, s[6:7]
	s_add_i32 s63, s3, 0x12000
	s_mov_b32 m0, s63
	s_nop 0
	global_load_lds_dwordx4 v0, s[14:15]
	s_add_u32 s14, s14, s34
	s_addc_u32 s15, s15, s35
	s_add_u32 s20, s14, s34
	s_addc_u32 s21, s15, s35
	s_add_i32 s64, s3, 0x14000
	s_mov_b32 m0, s64
	s_nop 0
	global_load_lds_dwordx4 v0, s[14:15]
	s_add_i32 s65, s3, 0x16000
	s_mov_b32 m0, s65
	s_nop 0
	global_load_lds_dwordx4 v0, s[20:21]
	s_add_u32 s20, s4, s52
	s_addc_u32 s21, s5, s53
	s_mov_b32 m0, s3
	s_nop 0
	global_load_lds_dwordx4 v128, s[4:5]
	s_add_i32 s66, s3, 0x2000
	s_mov_b32 m0, s66
	s_nop 0
	global_load_lds_dwordx4 v128, s[20:21]
	s_add_u32 s20, s20, s52
	s_addc_u32 s21, s21, s53
	s_add_u32 s22, s20, s52
	s_addc_u32 s23, s21, s53
	s_add_i32 s67, s3, 0x4000
	s_add_i32 s73, s3, 0x6000
	s_mov_b32 m0, s67
	s_nop 0
	global_load_lds_dwordx4 v128, s[20:21]
	s_cmp_eq_u32 s18, 1
	s_cselect_b64 s[20:21], -1, 0
	s_mov_b32 m0, s73
	s_nop 0
	global_load_lds_dwordx4 v128, s[22:23]
	v_writelane_b32 v254, s20, 17
	s_cmp_lg_u32 s18, 1
	s_nop 0
	v_writelane_b32 v254, s21, 18
	s_cbranch_scc1 .LBB0_1011
	s_barrier
